# fused-epilogue P7/P10: hoist serialized residual-row loads, drop redundant L1 invalidate in stat exchange
# speedup vs baseline: 1.0041x; 1.0041x over previous
;     __device__ __forceinline__ void fused(f32x4 (&acc)[2][2][4][2], const Unit& u, int wr, int wc, int fr, int fq, LAS unsigned char* lds, int tid) const {
;     ...
;         if (tid == 0) { __hip_atomic_fetch_add(cnt + u.pm, 1u, __ATOMIC_RELAXED, __HIP_MEMORY_SCOPE_AGENT);
;             unsigned sp = 0; while (__hip_atomic_load(cnt + u.pm, __ATOMIC_RELAXED, __HIP_MEMORY_SCOPE_AGENT) < 4u) { __builtin_amdgcn_s_sleep(1); if (++sp > (1u << 24)) break; }
;             __builtin_amdgcn_fence(__ATOMIC_ACQUIRE, "agent"); asm volatile("s_waitcnt vmcnt(0)" ::: "memory"); }
.LBB0_519:
	s_or_b64 exec, exec, s[2:3]
	s_nop 0
	s_waitcnt vmcnt(0)

;     __device__ __forceinline__ void fused(f32x4 (&acc)[2][2][4][2], const Unit& u, int wr, int wc, int fr, int fq, LAS unsigned char* lds, int tid) const {
;     ...
;             f32x4 gv[2][2];
; #pragma unroll
;             for (int bj = 0; bj < 2; ++bj)
; #pragma unroll
;                 for (int n = 0; n < 2; ++n) gv[bj][n] = *(const f32x4*)(gate + (size_t)cls * MODLD + col0 + bj * HALF + n * 4) * coef;
; #pragma unroll
;             for (int ai = 0; ai < 2; ++ai)
; #pragma unroll
;                 for (int m = 0; m < 4; ++m) { const size_t off = (size_t)(ai * HALF + wr * 64 + m * 16 + fr) * DM + col0; float q = 0.f;
; #pragma unroll
;                     for (int bj = 0; bj < 2; ++bj) { f32x4 b0, b1;
;                         if (BBF) { const u32x4 w = *(const u32x4*)(xb_ + off + bj * HALF);
;                             b0 = (f32x4){__uint_as_float(w.x << 16), __uint_as_float(w.x & 0xffff0000u), __uint_as_float(w.y << 16), __uint_as_float(w.y & 0xffff0000u)};
;                             b1 = (f32x4){__uint_as_float(w.z << 16), __uint_as_float(w.z & 0xffff0000u), __uint_as_float(w.w << 16), __uint_as_float(w.w & 0xffff0000u)}; }
;                         else { b0 = __builtin_nontemporal_load((const f32x4*)(bs_ + off + bj * HALF)); b1 = __builtin_nontemporal_load((const f32x4*)(bs_ + off + bj * HALF + 4)); }
;                         const f32x4 x0 = b0 + gv[bj][0] * acc[ai][bj][m][0], x1 = b1 + gv[bj][1] * acc[ai][bj][m][1]; acc[ai][bj][m][0] = x0; acc[ai][bj][m][1] = x1;
;                         q += ((x0[0] * x0[0] + x0[1] * x0[1]) + (x0[2] * x0[2] + x0[3] * x0[3])) + ((x1[0] * x1[0] + x1[1] * x1[1]) + (x1[2] * x1[2] + x1[3] * x1[3])); }
;                     q += __shfl_xor(q, 16); q += __shfl_xor(q, 32);
;                     if (fq == 0) P[(ai * HALF + wr * 64 + m * 16 + fr) * 4 + wc] = q;
;                     asm volatile("" ::: "memory"); }
.LBB0_1108:
	s_add_u32 s14, s94, 0x6000
	s_addc_u32 s15, s95, 0
	s_add_u32 s22, s94, 0x7000
	s_addc_u32 s23, s95, 0
	s_add_u32 s24, s94, 0x8000
	s_addc_u32 s25, s95, 0
	s_add_u32 s28, s94, 0xff40000
	s_addc_u32 s29, s95, 0
	s_add_u32 s30, s94, 0x83900
	v_readlane_b32 s20, v254, 60
	s_addc_u32 s31, s95, 0
	s_mov_b32 s2, 1.0
	s_mov_b64 s[8:9], s[18:19]
	s_mov_b64 s[10:11], s[92:93]
	s_mov_b64 s[26:27], s[82:83]
	v_readlane_b32 s21, v254, 61
	s_mov_b64 s[12:13], s[92:93]
	s_waitcnt vmcnt(0)
	s_barrier
	s_ashr_i32 s7, s6, 31
	s_lshr_b32 s12, s7, 28
	s_add_i32 s12, s6, s12
	s_lshl_b32 s3, s1, 5
	s_ashr_i32 s13, s12, 4
	s_lshl_b32 s12, s0, 8
	s_lshl_b64 s[10:11], s[6:7], 19
	s_or_b32 s3, s12, s3
	s_mul_hi_i32 s12, s13, 0x9000
	s_mul_i32 s13, s13, 0x9000
	v_lshl_or_b32 v132, v150, 3, s3
	s_add_u32 s14, s14, s13
	s_addc_u32 s15, s15, s12
	v_ashrrev_i32_e32 v133, 31, v132
	v_lshl_add_u64 v[130:131], v[132:133], 2, s[14:15]
	s_add_u32 s14, s20, s10
	s_addc_u32 s15, s21, s11
	v_ashrrev_i32_e32 v129, 31, v128
	global_load_dwordx4 v[134:137], v[130:131], off
	global_load_dwordx4 v[138:141], v[130:131], off offset:16
	global_load_dwordx4 v[146:149], v[130:131], off offset:512
	global_load_dwordx4 v[152:155], v[130:131], off offset:528
	v_lshl_add_u64 v[172:173], v[132:133], 1, s[14:15]
	v_lshlrev_b64 v[130:131], 11, v[128:129]
	v_lshl_add_u64 v[130:131], v[172:173], 0, v[130:131]
	global_load_dwordx4 v[156:159], v[130:131], off
	global_load_dwordx4 v[160:163], v[130:131], off offset:256
	v_mov_b32_e32 v248, v130
	v_mov_b32_e32 v249, v131
	s_mov_b32 s99, 0
	s_mov_b32 s98, 0x8000
	v_lshl_add_u64 v[246:247], v[248:249], 0, s[98:99]
	global_load_dwordx4 v[206:209], v[246:247], off
	global_load_dwordx4 v[210:213], v[246:247], off offset:256
	s_mov_b32 s98, 0x10000
	v_lshl_add_u64 v[246:247], v[248:249], 0, s[98:99]
	global_load_dwordx4 v[214:217], v[246:247], off
	global_load_dwordx4 v[218:221], v[246:247], off offset:256
	s_mov_b32 s98, 0x18000
	v_lshl_add_u64 v[246:247], v[248:249], 0, s[98:99]
	global_load_dwordx4 v[222:225], v[246:247], off
	global_load_dwordx4 v[226:229], v[246:247], off offset:256
	s_mov_b32 s98, 0x40000
	v_lshl_add_u64 v[246:247], v[248:249], 0, s[98:99]
	global_load_dwordx4 v[230:233], v[246:247], off
	global_load_dwordx4 v[234:237], v[246:247], off offset:256
	s_mov_b32 s98, 0x48000
	v_lshl_add_u64 v[246:247], v[248:249], 0, s[98:99]
	global_load_dwordx4 v[238:241], v[246:247], off
	global_load_dwordx4 v[242:245], v[246:247], off offset:256
	v_mbcnt_lo_u32_b32 v142, -1, 0
	v_mbcnt_hi_u32_b32 v151, -1, v142
	v_and_b32_e32 v143, 64, v151
	v_xor_b32_e32 v142, 16, v151
	v_add_u32_e32 v164, 64, v143
	v_cmp_lt_i32_e32 vcc, v142, v164
	s_lshl_b32 s1, s1, 2
	s_add_i32 s1, s1, 0
	v_cndmask_b32_e32 v142, v151, v142, vcc
	v_lshlrev_b32_e32 v191, 2, v142
	s_waitcnt vmcnt(10) lgkmcnt(0)
	v_pk_mul_f32 v[178:179], v[134:135], s[2:3] op_sel_hi:[1,0]
	v_pk_mul_f32 v[174:175], v[136:137], s[2:3] op_sel_hi:[1,0]
	v_pk_mul_f32 v[176:177], v[138:139], s[2:3] op_sel_hi:[1,0]
	v_pk_mul_f32 v[188:189], v[140:141], s[2:3] op_sel_hi:[1,0]
	v_pk_mul_f32 v[184:185], s[2:3], v[146:147] op_sel_hi:[0,1]
	v_pk_mul_f32 v[186:187], s[2:3], v[148:149] op_sel_hi:[0,1]
	v_lshlrev_b32_e32 v134, 16, v156
	v_and_b32_e32 v135, 0xffff0000, v156
	v_lshlrev_b32_e32 v136, 16, v157
	v_and_b32_e32 v137, 0xffff0000, v157
	v_lshlrev_b32_e32 v138, 16, v158
	v_and_b32_e32 v139, 0xffff0000, v158
	v_lshlrev_b32_e32 v140, 16, v159
	v_and_b32_e32 v141, 0xffff0000, v159
	v_pk_mul_f32 v[180:181], s[2:3], v[152:153] op_sel_hi:[0,1]
	v_pk_mul_f32 v[182:183], s[2:3], v[154:155] op_sel_hi:[0,1]
	v_lshlrev_b32_e32 v142, 16, v160
	v_and_b32_e32 v143, 0xffff0000, v160
	v_lshlrev_b32_e32 v146, 16, v161
	v_and_b32_e32 v147, 0xffff0000, v161
	v_lshlrev_b32_e32 v148, 16, v162
	v_and_b32_e32 v149, 0xffff0000, v162
	v_lshlrev_b32_e32 v152, 16, v163
	v_and_b32_e32 v153, 0xffff0000, v163
	v_pk_fma_f32 v[126:127], v[126:127], v[174:175], v[136:137]
	v_pk_fma_f32 v[134:135], v[124:125], v[178:179], v[134:135]
	v_pk_fma_f32 v[122:123], v[122:123], v[188:189], v[140:141]
	v_pk_fma_f32 v[124:125], v[120:121], v[176:177], v[138:139]
	v_pk_fma_f32 v[118:119], v[118:119], v[186:187], v[146:147]
	v_pk_fma_f32 v[116:117], v[116:117], v[184:185], v[142:143]
	v_pk_fma_f32 v[114:115], v[114:115], v[182:183], v[152:153]
	v_pk_fma_f32 v[120:121], v[112:113], v[180:181], v[148:149]
	v_mul_f32_e32 v112, v135, v135
	v_mul_f32_e32 v113, v127, v127
	v_mul_f32_e32 v136, v125, v125
	v_mul_f32_e32 v137, v123, v123
	v_mul_f32_e32 v138, v117, v117
	v_mul_f32_e32 v139, v119, v119
	v_mul_f32_e32 v140, v121, v121
	v_mul_f32_e32 v141, v115, v115
	v_fmac_f32_e32 v112, v134, v134
	v_fmac_f32_e32 v113, v126, v126
	v_fmac_f32_e32 v136, v124, v124
	v_fmac_f32_e32 v137, v122, v122
	v_fmac_f32_e32 v138, v116, v116
	v_fmac_f32_e32 v139, v118, v118
	v_fmac_f32_e32 v140, v120, v120
	v_fmac_f32_e32 v141, v114, v114
	v_add_f32_e32 v112, v112, v113
	v_add_f32_e32 v113, v136, v137
	v_add_f32_e32 v136, v138, v139
	v_add_f32_e32 v112, v112, v113
	v_add_f32_e32 v113, v140, v141
	v_add_f32_e32 v113, v136, v113
	v_add_f32_e32 v112, v112, v113
	ds_bpermute_b32 v113, v191, v112
	v_xor_b32_e32 v136, 32, v151
	v_cmp_lt_i32_e32 vcc, v136, v164
	s_waitcnt lgkmcnt(0)
	v_add_f32_e32 v112, v112, v113
	v_cndmask_b32_e32 v136, v151, v136, vcc
	v_lshlrev_b32_e32 v192, 2, v136
	ds_bpermute_b32 v113, v192, v112
	v_cmp_eq_u32_e32 vcc, 0, v150
	s_and_saveexec_b64 s[2:3], vcc
	s_cbranch_execz .LBB0_1110
	v_lshl_add_u32 v136, v128, 4, s1
	s_waitcnt lgkmcnt(0)
	v_add_f32_e32 v112, v112, v113
	ds_write_b32 v136, v112
;     __device__ __forceinline__ void fused(f32x4 (&acc)[2][2][4][2], const Unit& u, int wr, int wc, int fr, int fq, LAS unsigned char* lds, int tid) const {
;     ...
;                 for (int m = 0; m < 4; ++m) { const size_t off = (size_t)(ai * HALF + wr * 64 + m * 16 + fr) * DM + col0; float q = 0.f;
; #pragma unroll
;                     for (int bj = 0; bj < 2; ++bj) { f32x4 b0, b1;
;                         if (BBF) { const u32x4 w = *(const u32x4*)(xb_ + off + bj * HALF);
;                             b0 = (f32x4){__uint_as_float(w.x << 16), __uint_as_float(w.x & 0xffff0000u), __uint_as_float(w.y << 16), __uint_as_float(w.y & 0xffff0000u)};
;                             b1 = (f32x4){__uint_as_float(w.z << 16), __uint_as_float(w.z & 0xffff0000u), __uint_as_float(w.w << 16), __uint_as_float(w.w & 0xffff0000u)}; }
;                         else { b0 = __builtin_nontemporal_load((const f32x4*)(bs_ + off + bj * HALF)); b1 = __builtin_nontemporal_load((const f32x4*)(bs_ + off + bj * HALF + 4)); }
;                         const f32x4 x0 = b0 + gv[bj][0] * acc[ai][bj][m][0], x1 = b1 + gv[bj][1] * acc[ai][bj][m][1]; acc[ai][bj][m][0] = x0; acc[ai][bj][m][1] = x1;
;                         q += ((x0[0] * x0[0] + x0[1] * x0[1]) + (x0[2] * x0[2] + x0[3] * x0[3])) + ((x1[0] * x1[0] + x1[1] * x1[1]) + (x1[2] * x1[2] + x1[3] * x1[3])); }
;                     q += __shfl_xor(q, 16); q += __shfl_xor(q, 32);
;                     if (fq == 0) P[(ai * HALF + wr * 64 + m * 16 + fr) * 4 + wc] = q;
;                     asm volatile("" ::: "memory"); }
.LBB0_1110:
	s_or_b64 exec, exec, s[2:3]
	v_or_b32_e32 v138, 16, v128
	v_ashrrev_i32_e32 v139, 31, v138
	s_waitcnt lgkmcnt(0)
	v_lshlrev_b64 v[112:113], 11, v[138:139]
	v_lshl_add_u64 v[112:113], v[172:173], 0, v[112:113]
	s_waitcnt vmcnt(8) lgkmcnt(0)
	v_lshlrev_b32_e32 v136, 16, v206
	v_and_b32_e32 v137, 0xffff0000, v206
	v_lshlrev_b32_e32 v140, 16, v207
	v_and_b32_e32 v141, 0xffff0000, v207
	v_lshlrev_b32_e32 v150, 16, v208
	v_and_b32_e32 v151, 0xffff0000, v208
	v_lshlrev_b32_e32 v142, 16, v209
	v_and_b32_e32 v143, 0xffff0000, v209
	v_lshlrev_b32_e32 v152, 16, v210
	v_and_b32_e32 v153, 0xffff0000, v210
	v_lshlrev_b32_e32 v146, 16, v211
	v_and_b32_e32 v147, 0xffff0000, v211
	v_lshlrev_b32_e32 v154, 16, v212
	v_and_b32_e32 v155, 0xffff0000, v212
	v_lshlrev_b32_e32 v148, 16, v213
	v_and_b32_e32 v149, 0xffff0000, v213
	s_mov_b32 s98, 0x50000
	v_lshl_add_u64 v[246:247], v[248:249], 0, s[98:99]
	global_load_dwordx4 v[206:209], v[246:247], off
	global_load_dwordx4 v[210:213], v[246:247], off offset:256
	v_pk_fma_f32 v[110:111], v[110:111], v[174:175], v[140:141]
	v_pk_fma_f32 v[136:137], v[108:109], v[178:179], v[136:137]
	v_pk_fma_f32 v[106:107], v[106:107], v[188:189], v[142:143]
	v_pk_fma_f32 v[108:109], v[104:105], v[176:177], v[150:151]
	v_pk_fma_f32 v[102:103], v[102:103], v[186:187], v[146:147]
	v_pk_fma_f32 v[100:101], v[100:101], v[184:185], v[152:153]
	v_pk_fma_f32 v[98:99], v[98:99], v[182:183], v[148:149]
	v_pk_fma_f32 v[104:105], v[96:97], v[180:181], v[154:155]
	v_mul_f32_e32 v96, v137, v137
	v_mul_f32_e32 v97, v111, v111
	v_mul_f32_e32 v140, v109, v109
	v_mul_f32_e32 v141, v107, v107
	v_mul_f32_e32 v142, v101, v101
	v_mul_f32_e32 v143, v103, v103
	v_mul_f32_e32 v146, v105, v105
	v_mul_f32_e32 v147, v99, v99
	v_fmac_f32_e32 v96, v136, v136
	v_fmac_f32_e32 v97, v110, v110
	v_fmac_f32_e32 v140, v108, v108
	v_fmac_f32_e32 v141, v106, v106
	v_fmac_f32_e32 v142, v100, v100
	v_fmac_f32_e32 v143, v102, v102
	v_fmac_f32_e32 v146, v104, v104
	v_fmac_f32_e32 v147, v98, v98
	v_add_f32_e32 v96, v96, v97
	v_add_f32_e32 v97, v140, v141
	v_add_f32_e32 v140, v142, v143
	v_add_f32_e32 v141, v146, v147
	v_add_f32_e32 v96, v96, v97
	v_add_f32_e32 v97, v140, v141
	v_add_f32_e32 v96, v96, v97
	ds_bpermute_b32 v97, v191, v96
	s_waitcnt lgkmcnt(0)
	v_add_f32_e32 v96, v96, v97
	ds_bpermute_b32 v97, v192, v96
	s_and_saveexec_b64 s[2:3], vcc
	s_cbranch_execz .LBB0_1112
	v_lshl_add_u32 v140, v138, 4, s1
	s_waitcnt lgkmcnt(0)
	v_add_f32_e32 v96, v96, v97
	ds_write_b32 v140, v96
.LBB0_1112:
	s_or_b64 exec, exec, s[2:3]
	v_or_b32_e32 v146, 32, v128
	v_ashrrev_i32_e32 v147, 31, v146
	s_waitcnt lgkmcnt(0)
	v_lshlrev_b64 v[96:97], 11, v[146:147]
	v_lshl_add_u64 v[96:97], v[172:173], 0, v[96:97]
	s_waitcnt vmcnt(8) lgkmcnt(0)
	v_lshlrev_b32_e32 v152, 16, v214
	v_and_b32_e32 v153, 0xffff0000, v214
	v_lshlrev_b32_e32 v140, 16, v215
	v_and_b32_e32 v141, 0xffff0000, v215
	v_lshlrev_b32_e32 v154, 16, v216
	v_and_b32_e32 v155, 0xffff0000, v216
	v_lshlrev_b32_e32 v142, 16, v217
	v_and_b32_e32 v143, 0xffff0000, v217
	v_lshlrev_b32_e32 v156, 16, v218
	v_and_b32_e32 v157, 0xffff0000, v218
	v_lshlrev_b32_e32 v148, 16, v219
	v_and_b32_e32 v149, 0xffff0000, v219
	v_lshlrev_b32_e32 v158, 16, v220
	v_and_b32_e32 v159, 0xffff0000, v220
	v_lshlrev_b32_e32 v150, 16, v221
	v_and_b32_e32 v151, 0xffff0000, v221
	s_mov_b32 s98, 0x58000
	v_lshl_add_u64 v[246:247], v[248:249], 0, s[98:99]
	global_load_dwordx4 v[214:217], v[246:247], off
	global_load_dwordx4 v[218:221], v[246:247], off offset:256
	v_pk_fma_f32 v[94:95], v[94:95], v[174:175], v[140:141]
	v_pk_fma_f32 v[140:141], v[92:93], v[178:179], v[152:153]
	v_pk_fma_f32 v[90:91], v[90:91], v[188:189], v[142:143]
	v_pk_fma_f32 v[92:93], v[88:89], v[176:177], v[154:155]
	v_pk_fma_f32 v[86:87], v[86:87], v[186:187], v[148:149]
	v_pk_fma_f32 v[84:85], v[84:85], v[184:185], v[156:157]
	v_pk_fma_f32 v[82:83], v[82:83], v[182:183], v[150:151]
	v_pk_fma_f32 v[88:89], v[80:81], v[180:181], v[158:159]
	v_mul_f32_e32 v80, v141, v141
	v_mul_f32_e32 v81, v95, v95
	v_mul_f32_e32 v142, v93, v93
	v_mul_f32_e32 v143, v91, v91
	v_mul_f32_e32 v148, v85, v85
	v_mul_f32_e32 v149, v87, v87
	v_mul_f32_e32 v150, v89, v89
	v_mul_f32_e32 v151, v83, v83
	v_fmac_f32_e32 v80, v140, v140
	v_fmac_f32_e32 v81, v94, v94
	v_fmac_f32_e32 v142, v92, v92
	v_fmac_f32_e32 v143, v90, v90
	v_fmac_f32_e32 v148, v84, v84
	v_fmac_f32_e32 v149, v86, v86
	v_fmac_f32_e32 v150, v88, v88
	v_fmac_f32_e32 v151, v82, v82
	v_add_f32_e32 v80, v80, v81
	v_add_f32_e32 v81, v142, v143
	v_add_f32_e32 v142, v148, v149
	v_add_f32_e32 v143, v150, v151
	v_add_f32_e32 v80, v80, v81
	v_add_f32_e32 v81, v142, v143
	v_add_f32_e32 v80, v80, v81
	ds_bpermute_b32 v81, v191, v80
	s_waitcnt lgkmcnt(0)
	v_add_f32_e32 v80, v80, v81
	ds_bpermute_b32 v81, v192, v80
	s_and_saveexec_b64 s[2:3], vcc
	s_cbranch_execz .LBB0_1114
	v_lshl_add_u32 v142, v146, 4, s1
	s_waitcnt lgkmcnt(0)
	v_add_f32_e32 v80, v80, v81
	ds_write_b32 v142, v80
;     __device__ __forceinline__ void fused(f32x4 (&acc)[2][2][4][2], const Unit& u, int wr, int wc, int fr, int fq, LAS unsigned char* lds, int tid) const {
;     ...
;                 for (int m = 0; m < 4; ++m) { const size_t off = (size_t)(ai * HALF + wr * 64 + m * 16 + fr) * DM + col0; float q = 0.f;
; #pragma unroll
;                     for (int bj = 0; bj < 2; ++bj) { f32x4 b0, b1;
;                         if (BBF) { const u32x4 w = *(const u32x4*)(xb_ + off + bj * HALF);
;                             b0 = (f32x4){__uint_as_float(w.x << 16), __uint_as_float(w.x & 0xffff0000u), __uint_as_float(w.y << 16), __uint_as_float(w.y & 0xffff0000u)};
;                             b1 = (f32x4){__uint_as_float(w.z << 16), __uint_as_float(w.z & 0xffff0000u), __uint_as_float(w.w << 16), __uint_as_float(w.w & 0xffff0000u)}; }
;                         else { b0 = __builtin_nontemporal_load((const f32x4*)(bs_ + off + bj * HALF)); b1 = __builtin_nontemporal_load((const f32x4*)(bs_ + off + bj * HALF + 4)); }
;                         const f32x4 x0 = b0 + gv[bj][0] * acc[ai][bj][m][0], x1 = b1 + gv[bj][1] * acc[ai][bj][m][1]; acc[ai][bj][m][0] = x0; acc[ai][bj][m][1] = x1;
;                         q += ((x0[0] * x0[0] + x0[1] * x0[1]) + (x0[2] * x0[2] + x0[3] * x0[3])) + ((x1[0] * x1[0] + x1[1] * x1[1]) + (x1[2] * x1[2] + x1[3] * x1[3])); }
;                     q += __shfl_xor(q, 16); q += __shfl_xor(q, 32);
;                     if (fq == 0) P[(ai * HALF + wr * 64 + m * 16 + fr) * 4 + wc] = q;
;                     asm volatile("" ::: "memory"); }
.LBB0_1114:
	s_or_b64 exec, exec, s[2:3]
	v_or_b32_e32 v142, 48, v128
	v_ashrrev_i32_e32 v143, 31, v142
	s_waitcnt lgkmcnt(0)
	v_lshlrev_b64 v[80:81], 11, v[142:143]
	v_lshl_add_u64 v[80:81], v[172:173], 0, v[80:81]
	s_waitcnt vmcnt(8) lgkmcnt(0)
	v_lshlrev_b32_e32 v156, 16, v222
	v_and_b32_e32 v157, 0xffff0000, v222
	v_lshlrev_b32_e32 v148, 16, v223
	v_and_b32_e32 v149, 0xffff0000, v223
	v_lshlrev_b32_e32 v158, 16, v224
	v_and_b32_e32 v159, 0xffff0000, v224
	v_lshlrev_b32_e32 v150, 16, v225
	v_and_b32_e32 v151, 0xffff0000, v225
	v_lshlrev_b32_e32 v160, 16, v226
	v_and_b32_e32 v161, 0xffff0000, v226
	v_lshlrev_b32_e32 v152, 16, v227
	v_and_b32_e32 v153, 0xffff0000, v227
	v_lshlrev_b32_e32 v162, 16, v228
	v_and_b32_e32 v163, 0xffff0000, v228
	v_lshlrev_b32_e32 v154, 16, v229
	v_and_b32_e32 v155, 0xffff0000, v229
	v_pk_fma_f32 v[78:79], v[78:79], v[174:175], v[148:149]
	v_pk_fma_f32 v[148:149], v[76:77], v[178:179], v[156:157]
	v_pk_fma_f32 v[74:75], v[74:75], v[188:189], v[150:151]
	v_pk_fma_f32 v[76:77], v[72:73], v[176:177], v[158:159]
	v_pk_fma_f32 v[70:71], v[70:71], v[186:187], v[152:153]
	v_pk_fma_f32 v[68:69], v[68:69], v[184:185], v[160:161]
	v_pk_fma_f32 v[66:67], v[66:67], v[182:183], v[154:155]
	v_pk_fma_f32 v[72:73], v[64:65], v[180:181], v[162:163]
	v_mul_f32_e32 v64, v149, v149
	v_mul_f32_e32 v65, v79, v79
	v_mul_f32_e32 v150, v77, v77
	v_mul_f32_e32 v151, v75, v75
	v_mul_f32_e32 v152, v69, v69
	v_mul_f32_e32 v153, v71, v71
	v_mul_f32_e32 v154, v73, v73
	v_mul_f32_e32 v155, v67, v67
	v_fmac_f32_e32 v64, v148, v148
	v_fmac_f32_e32 v65, v78, v78
	v_fmac_f32_e32 v150, v76, v76
	v_fmac_f32_e32 v151, v74, v74
	v_fmac_f32_e32 v152, v68, v68
	v_fmac_f32_e32 v153, v70, v70
	v_fmac_f32_e32 v154, v72, v72
	v_fmac_f32_e32 v155, v66, v66
	v_add_f32_e32 v64, v64, v65
	v_add_f32_e32 v65, v150, v151
	v_add_f32_e32 v150, v152, v153
	v_add_f32_e32 v151, v154, v155
	v_add_f32_e32 v64, v64, v65
	v_add_f32_e32 v65, v150, v151
	v_add_f32_e32 v64, v64, v65
	ds_bpermute_b32 v65, v191, v64
	s_waitcnt lgkmcnt(0)
	v_add_f32_e32 v64, v64, v65
	ds_bpermute_b32 v65, v192, v64
	s_and_saveexec_b64 s[2:3], vcc
	s_cbranch_execz .LBB0_1116
	v_lshl_add_u32 v150, v142, 4, s1
	s_waitcnt lgkmcnt(0)
	v_add_f32_e32 v64, v64, v65
	ds_write_b32 v150, v64
.LBB0_1116:
	s_or_b64 exec, exec, s[2:3]
	v_add_u32_e32 v150, 0x80, v128
	v_ashrrev_i32_e32 v151, 31, v150
	s_waitcnt lgkmcnt(0)
	v_lshlrev_b64 v[64:65], 11, v[150:151]
	v_lshl_add_u64 v[64:65], v[172:173], 0, v[64:65]
	s_waitcnt vmcnt(6) lgkmcnt(0)
	v_lshlrev_b32_e32 v160, 16, v230
	v_and_b32_e32 v161, 0xffff0000, v230
	v_lshlrev_b32_e32 v152, 16, v231
	v_and_b32_e32 v153, 0xffff0000, v231
	v_lshlrev_b32_e32 v162, 16, v232
	v_and_b32_e32 v163, 0xffff0000, v232
	v_lshlrev_b32_e32 v154, 16, v233
	v_and_b32_e32 v155, 0xffff0000, v233
	v_lshlrev_b32_e32 v164, 16, v234
	v_and_b32_e32 v165, 0xffff0000, v234
	v_lshlrev_b32_e32 v156, 16, v235
	v_and_b32_e32 v157, 0xffff0000, v235
	v_lshlrev_b32_e32 v166, 16, v236
	v_and_b32_e32 v167, 0xffff0000, v236
	v_lshlrev_b32_e32 v158, 16, v237
	v_and_b32_e32 v159, 0xffff0000, v237
	v_pk_fma_f32 v[62:63], v[62:63], v[174:175], v[152:153]
	v_pk_fma_f32 v[152:153], v[60:61], v[178:179], v[160:161]
	v_pk_fma_f32 v[58:59], v[58:59], v[188:189], v[154:155]
	v_pk_fma_f32 v[60:61], v[56:57], v[176:177], v[162:163]
	v_pk_fma_f32 v[54:55], v[54:55], v[186:187], v[156:157]
	v_pk_fma_f32 v[52:53], v[52:53], v[184:185], v[164:165]
	v_pk_fma_f32 v[50:51], v[50:51], v[182:183], v[158:159]
	v_pk_fma_f32 v[56:57], v[48:49], v[180:181], v[166:167]
	v_mul_f32_e32 v48, v153, v153
	v_mul_f32_e32 v49, v63, v63
	v_mul_f32_e32 v154, v61, v61
	v_mul_f32_e32 v155, v59, v59
	v_mul_f32_e32 v156, v53, v53
	v_mul_f32_e32 v157, v55, v55
	v_mul_f32_e32 v158, v57, v57
	v_mul_f32_e32 v159, v51, v51
	v_fmac_f32_e32 v48, v152, v152
	v_fmac_f32_e32 v49, v62, v62
	v_fmac_f32_e32 v154, v60, v60
	v_fmac_f32_e32 v155, v58, v58
	v_fmac_f32_e32 v156, v52, v52
	v_fmac_f32_e32 v157, v54, v54
	v_fmac_f32_e32 v158, v56, v56
	v_fmac_f32_e32 v159, v50, v50
	v_add_f32_e32 v48, v48, v49
	v_add_f32_e32 v49, v154, v155
	v_add_f32_e32 v154, v156, v157
	v_add_f32_e32 v155, v158, v159
	v_add_f32_e32 v48, v48, v49
	v_add_f32_e32 v49, v154, v155
	v_add_f32_e32 v48, v48, v49
	ds_bpermute_b32 v49, v191, v48
	s_waitcnt lgkmcnt(0)
	v_add_f32_e32 v48, v48, v49
	ds_bpermute_b32 v49, v192, v48
	s_and_saveexec_b64 s[2:3], vcc
	s_cbranch_execz .LBB0_1118
	v_lshl_add_u32 v154, v150, 4, s1
	s_waitcnt lgkmcnt(0)
	v_add_f32_e32 v48, v48, v49
	ds_write_b32 v154, v48
;     __device__ __forceinline__ void fused(f32x4 (&acc)[2][2][4][2], const Unit& u, int wr, int wc, int fr, int fq, LAS unsigned char* lds, int tid) const {
;     ...
;                 for (int m = 0; m < 4; ++m) { const size_t off = (size_t)(ai * HALF + wr * 64 + m * 16 + fr) * DM + col0; float q = 0.f;
; #pragma unroll
;                     for (int bj = 0; bj < 2; ++bj) { f32x4 b0, b1;
;                         if (BBF) { const u32x4 w = *(const u32x4*)(xb_ + off + bj * HALF);
;                             b0 = (f32x4){__uint_as_float(w.x << 16), __uint_as_float(w.x & 0xffff0000u), __uint_as_float(w.y << 16), __uint_as_float(w.y & 0xffff0000u)};
;                             b1 = (f32x4){__uint_as_float(w.z << 16), __uint_as_float(w.z & 0xffff0000u), __uint_as_float(w.w << 16), __uint_as_float(w.w & 0xffff0000u)}; }
;                         else { b0 = __builtin_nontemporal_load((const f32x4*)(bs_ + off + bj * HALF)); b1 = __builtin_nontemporal_load((const f32x4*)(bs_ + off + bj * HALF + 4)); }
;                         const f32x4 x0 = b0 + gv[bj][0] * acc[ai][bj][m][0], x1 = b1 + gv[bj][1] * acc[ai][bj][m][1]; acc[ai][bj][m][0] = x0; acc[ai][bj][m][1] = x1;
;                         q += ((x0[0] * x0[0] + x0[1] * x0[1]) + (x0[2] * x0[2] + x0[3] * x0[3])) + ((x1[0] * x1[0] + x1[1] * x1[1]) + (x1[2] * x1[2] + x1[3] * x1[3])); }
;                     q += __shfl_xor(q, 16); q += __shfl_xor(q, 32);
;                     if (fq == 0) P[(ai * HALF + wr * 64 + m * 16 + fr) * 4 + wc] = q;
;                     asm volatile("" ::: "memory"); }
.LBB0_1118:
	s_or_b64 exec, exec, s[2:3]
	v_add_u32_e32 v154, 0x90, v128
	v_ashrrev_i32_e32 v155, 31, v154
	s_waitcnt lgkmcnt(0)
	v_lshlrev_b64 v[48:49], 11, v[154:155]
	v_lshl_add_u64 v[48:49], v[172:173], 0, v[48:49]
	s_waitcnt vmcnt(4) lgkmcnt(0)
	v_lshlrev_b32_e32 v164, 16, v238
	v_and_b32_e32 v165, 0xffff0000, v238
	v_lshlrev_b32_e32 v156, 16, v239
	v_and_b32_e32 v157, 0xffff0000, v239
	v_lshlrev_b32_e32 v166, 16, v240
	v_and_b32_e32 v167, 0xffff0000, v240
	v_lshlrev_b32_e32 v168, 16, v241
	v_and_b32_e32 v169, 0xffff0000, v241
	v_lshlrev_b32_e32 v170, 16, v242
	v_and_b32_e32 v171, 0xffff0000, v242
	v_lshlrev_b32_e32 v160, 16, v243
	v_and_b32_e32 v161, 0xffff0000, v243
	v_lshlrev_b32_e32 v194, 16, v244
	v_and_b32_e32 v195, 0xffff0000, v244
	v_lshlrev_b32_e32 v162, 16, v245
	v_and_b32_e32 v163, 0xffff0000, v245
	v_pk_fma_f32 v[46:47], v[46:47], v[174:175], v[156:157]
	v_pk_fma_f32 v[158:159], v[44:45], v[178:179], v[164:165]
	v_pk_fma_f32 v[44:45], v[42:43], v[188:189], v[168:169]
	v_pk_fma_f32 v[156:157], v[40:41], v[176:177], v[166:167]
	v_pk_fma_f32 v[38:39], v[38:39], v[186:187], v[160:161]
	v_pk_fma_f32 v[36:37], v[36:37], v[184:185], v[170:171]
	v_pk_fma_f32 v[34:35], v[34:35], v[182:183], v[162:163]
	v_pk_fma_f32 v[40:41], v[32:33], v[180:181], v[194:195]
	v_mul_f32_e32 v32, v159, v159
	v_mul_f32_e32 v33, v47, v47
	v_mul_f32_e32 v42, v157, v157
	v_mul_f32_e32 v43, v45, v45
	v_mul_f32_e32 v160, v37, v37
	v_mul_f32_e32 v161, v39, v39
	v_mul_f32_e32 v162, v41, v41
	v_mul_f32_e32 v163, v35, v35
	v_fmac_f32_e32 v32, v158, v158
	v_fmac_f32_e32 v33, v46, v46
	v_fmac_f32_e32 v42, v156, v156
	v_fmac_f32_e32 v43, v44, v44
	v_fmac_f32_e32 v160, v36, v36
	v_fmac_f32_e32 v161, v38, v38
	v_fmac_f32_e32 v162, v40, v40
	v_fmac_f32_e32 v163, v34, v34
	v_add_f32_e32 v32, v32, v33
	v_add_f32_e32 v33, v42, v43
	v_add_f32_e32 v42, v160, v161
	v_add_f32_e32 v43, v162, v163
	v_add_f32_e32 v32, v32, v33
	v_add_f32_e32 v33, v42, v43
	v_add_f32_e32 v32, v32, v33
	ds_bpermute_b32 v33, v191, v32
	s_waitcnt lgkmcnt(0)
	v_add_f32_e32 v32, v32, v33
	ds_bpermute_b32 v33, v192, v32
	s_and_saveexec_b64 s[2:3], vcc
	s_cbranch_execz .LBB0_1120
	v_lshl_add_u32 v42, v154, 4, s1
	s_waitcnt lgkmcnt(0)
	v_add_f32_e32 v32, v32, v33
	ds_write_b32 v42, v32
.LBB0_1120:
	s_or_b64 exec, exec, s[2:3]
	v_add_u32_e32 v160, 0xa0, v128
	v_ashrrev_i32_e32 v161, 31, v160
	s_waitcnt lgkmcnt(0)
	v_lshlrev_b64 v[32:33], 11, v[160:161]
	v_lshl_add_u64 v[32:33], v[172:173], 0, v[32:33]
	s_waitcnt vmcnt(2) lgkmcnt(0)
	v_lshlrev_b32_e32 v42, 16, v206
	v_and_b32_e32 v43, 0xffff0000, v206
	v_lshlrev_b32_e32 v162, 16, v207
	v_and_b32_e32 v163, 0xffff0000, v207
	v_lshlrev_b32_e32 v170, 16, v208
	v_and_b32_e32 v171, 0xffff0000, v208
	v_lshlrev_b32_e32 v194, 16, v209
	v_and_b32_e32 v195, 0xffff0000, v209
	v_lshlrev_b32_e32 v196, 16, v210
	v_and_b32_e32 v197, 0xffff0000, v210
	v_lshlrev_b32_e32 v198, 16, v211
	v_and_b32_e32 v199, 0xffff0000, v211
	v_lshlrev_b32_e32 v202, 16, v212
	v_and_b32_e32 v203, 0xffff0000, v212
	v_lshlrev_b32_e32 v204, 16, v213
	v_and_b32_e32 v205, 0xffff0000, v213
	v_pk_fma_f32 v[164:165], v[30:31], v[174:175], v[162:163]
	v_pk_fma_f32 v[168:169], v[28:29], v[178:179], v[42:43]
	v_pk_fma_f32 v[162:163], v[26:27], v[188:189], v[194:195]
	v_pk_fma_f32 v[166:167], v[24:25], v[176:177], v[170:171]
	v_pk_fma_f32 v[22:23], v[22:23], v[186:187], v[198:199]
	v_pk_fma_f32 v[20:21], v[20:21], v[184:185], v[196:197]
	v_pk_fma_f32 v[18:19], v[18:19], v[182:183], v[204:205]
	v_pk_fma_f32 v[24:25], v[16:17], v[180:181], v[202:203]
	v_mul_f32_e32 v16, v169, v169
	v_mul_f32_e32 v17, v165, v165
	v_mul_f32_e32 v26, v167, v167
	v_mul_f32_e32 v27, v163, v163
	v_mul_f32_e32 v28, v21, v21
	v_mul_f32_e32 v29, v23, v23
	v_mul_f32_e32 v30, v25, v25
	v_mul_f32_e32 v31, v19, v19
	v_fmac_f32_e32 v16, v168, v168
	v_fmac_f32_e32 v17, v164, v164
	v_fmac_f32_e32 v26, v166, v166
	v_fmac_f32_e32 v27, v162, v162
	v_fmac_f32_e32 v28, v20, v20
	v_fmac_f32_e32 v29, v22, v22
	v_fmac_f32_e32 v30, v24, v24
	v_fmac_f32_e32 v31, v18, v18
	v_add_f32_e32 v16, v16, v17
	v_add_f32_e32 v17, v26, v27
	v_add_f32_e32 v26, v28, v29
	v_add_f32_e32 v27, v30, v31
	v_add_f32_e32 v16, v16, v17
	v_add_f32_e32 v17, v26, v27
	v_add_f32_e32 v16, v16, v17
	ds_bpermute_b32 v17, v191, v16
	s_waitcnt lgkmcnt(0)
	v_add_f32_e32 v16, v16, v17
	ds_bpermute_b32 v17, v192, v16
	s_and_saveexec_b64 s[2:3], vcc
	s_cbranch_execz .LBB0_1122
	v_lshl_add_u32 v26, v160, 4, s1
	s_waitcnt lgkmcnt(0)
	v_add_f32_e32 v16, v16, v17
	ds_write_b32 v26, v16
.LBB0_1122:
	s_or_b64 exec, exec, s[2:3]
	v_add_u32_e32 v170, 0xb0, v128
	v_ashrrev_i32_e32 v171, 31, v170
	s_waitcnt lgkmcnt(0)
	v_lshlrev_b64 v[16:17], 11, v[170:171]
	v_lshl_add_u64 v[16:17], v[172:173], 0, v[16:17]
	s_waitcnt vmcnt(0) lgkmcnt(0)
	v_lshlrev_b32_e32 v30, 16, v214
	v_and_b32_e32 v31, 0xffff0000, v214
	v_lshlrev_b32_e32 v26, 16, v215
	v_and_b32_e32 v27, 0xffff0000, v215
	v_lshlrev_b32_e32 v42, 16, v216
	v_and_b32_e32 v43, 0xffff0000, v216
	v_lshlrev_b32_e32 v28, 16, v217
	v_and_b32_e32 v29, 0xffff0000, v217
	v_lshlrev_b32_e32 v198, 16, v218
	v_and_b32_e32 v199, 0xffff0000, v218
	v_lshlrev_b32_e32 v194, 16, v219
	v_and_b32_e32 v195, 0xffff0000, v219
	v_lshlrev_b32_e32 v202, 16, v220
	v_and_b32_e32 v203, 0xffff0000, v220
	v_lshlrev_b32_e32 v196, 16, v221
	v_and_b32_e32 v197, 0xffff0000, v221
	v_pk_fma_f32 v[174:175], v[14:15], v[174:175], v[26:27]
	v_pk_fma_f32 v[178:179], v[12:13], v[178:179], v[30:31]
	v_pk_fma_f32 v[172:173], v[10:11], v[188:189], v[28:29]
	v_pk_fma_f32 v[176:177], v[8:9], v[176:177], v[42:43]
	v_pk_fma_f32 v[26:27], v[6:7], v[186:187], v[194:195]
	v_pk_fma_f32 v[30:31], v[4:5], v[184:185], v[198:199]
	v_pk_fma_f32 v[28:29], v[2:3], v[182:183], v[196:197]
	v_pk_fma_f32 v[42:43], v[0:1], v[180:181], v[202:203]
	v_mul_f32_e32 v0, v179, v179
	v_mul_f32_e32 v1, v175, v175
	v_mul_f32_e32 v2, v177, v177
	v_mul_f32_e32 v3, v173, v173
	v_mul_f32_e32 v4, v31, v31
	v_mul_f32_e32 v5, v27, v27
	v_mul_f32_e32 v6, v43, v43
	v_mul_f32_e32 v7, v29, v29
	v_fmac_f32_e32 v0, v178, v178
	v_fmac_f32_e32 v1, v174, v174
	v_fmac_f32_e32 v2, v176, v176
	v_fmac_f32_e32 v3, v172, v172
	v_fmac_f32_e32 v4, v30, v30
	v_fmac_f32_e32 v5, v26, v26
	v_fmac_f32_e32 v6, v42, v42
	v_fmac_f32_e32 v7, v28, v28
	v_add_f32_e32 v0, v0, v1
	v_add_f32_e32 v1, v2, v3
	v_add_f32_e32 v2, v4, v5
	v_add_f32_e32 v3, v6, v7
	v_add_f32_e32 v0, v0, v1
	v_add_f32_e32 v1, v2, v3
	v_add_f32_e32 v0, v0, v1
	ds_bpermute_b32 v1, v191, v0
	s_waitcnt lgkmcnt(0)
	v_add_f32_e32 v0, v0, v1
	ds_bpermute_b32 v1, v192, v0
	s_and_saveexec_b64 s[2:3], vcc
	s_cbranch_execz .LBB0_1124
	v_lshl_add_u32 v2, v170, 4, s1
	s_waitcnt lgkmcnt(0)
	v_add_f32_e32 v0, v0, v1
	ds_write_b32 v2, v0

;     __device__ __forceinline__ void fused(f32x4 (&acc)[2][2][4][2], const Unit& u, int wr, int wc, int fr, int fq, LAS unsigned char* lds, int tid) const {
;     ...
;         if (tid == 0) { __hip_atomic_fetch_add(cnt + u.pm, 1u, __ATOMIC_RELAXED, __HIP_MEMORY_SCOPE_AGENT);
;             unsigned sp = 0; while (__hip_atomic_load(cnt + u.pm, __ATOMIC_RELAXED, __HIP_MEMORY_SCOPE_AGENT) < 4u) { __builtin_amdgcn_s_sleep(1); if (++sp > (1u << 24)) break; }
;             __builtin_amdgcn_fence(__ATOMIC_ACQUIRE, "agent"); asm volatile("s_waitcnt vmcnt(0)" ::: "memory"); }
.LBB0_1148:
	s_or_b64 exec, exec, s[30:31]
	s_nop 0
	s_waitcnt vmcnt(0)

;     __device__ __forceinline__ void fused(f32x4 (&acc)[2][2][4][2], const Unit& u, int wr, int wc, int fr, int fq, LAS unsigned char* lds, int tid) const {
;     ...
;             f32x4 gv[2][2];
; #pragma unroll
;             for (int bj = 0; bj < 2; ++bj)
; #pragma unroll
;                 for (int n = 0; n < 2; ++n) gv[bj][n] = *(const f32x4*)(gate + (size_t)cls * MODLD + col0 + bj * HALF + n * 4) * coef;
; #pragma unroll
;             for (int ai = 0; ai < 2; ++ai)
; #pragma unroll
;                 for (int m = 0; m < 4; ++m) { const size_t off = (size_t)(ai * HALF + wr * 64 + m * 16 + fr) * DM + col0; float q = 0.f;
; #pragma unroll
;                     for (int bj = 0; bj < 2; ++bj) { f32x4 b0, b1;
;                         if (BBF) { const u32x4 w = *(const u32x4*)(xb_ + off + bj * HALF);
;                             b0 = (f32x4){__uint_as_float(w.x << 16), __uint_as_float(w.x & 0xffff0000u), __uint_as_float(w.y << 16), __uint_as_float(w.y & 0xffff0000u)};
;                             b1 = (f32x4){__uint_as_float(w.z << 16), __uint_as_float(w.z & 0xffff0000u), __uint_as_float(w.w << 16), __uint_as_float(w.w & 0xffff0000u)}; }
;                         else { b0 = __builtin_nontemporal_load((const f32x4*)(bs_ + off + bj * HALF)); b1 = __builtin_nontemporal_load((const f32x4*)(bs_ + off + bj * HALF + 4)); }
;                         const f32x4 x0 = b0 + gv[bj][0] * acc[ai][bj][m][0], x1 = b1 + gv[bj][1] * acc[ai][bj][m][1]; acc[ai][bj][m][0] = x0; acc[ai][bj][m][1] = x1;
;                         q += ((x0[0] * x0[0] + x0[1] * x0[1]) + (x0[2] * x0[2] + x0[3] * x0[3])) + ((x1[0] * x1[0] + x1[1] * x1[1]) + (x1[2] * x1[2] + x1[3] * x1[3])); }
;                     q += __shfl_xor(q, 16); q += __shfl_xor(q, 32);
;                     if (fq == 0) P[(ai * HALF + wr * 64 + m * 16 + fr) * 4 + wc] = q;
;                     asm volatile("" ::: "memory"); }
.LBB0_1400:
	s_add_u32 s12, s94, 0x9000
	s_addc_u32 s13, s95, 0
	s_add_u32 s10, s94, 0xff80000
	s_addc_u32 s11, s95, 0
	s_add_u32 s16, s94, 0x83a00
	v_readlane_b32 s26, v254, 60
	s_addc_u32 s17, s95, 0
	s_mov_b32 s18, 0.5
	s_mov_b64 s[14:15], 0
	s_mov_b64 s[20:21], s[92:93]
	s_mov_b64 s[22:23], 0
	s_mov_b64 s[24:25], 0
	s_mov_b64 s[2:3], s[92:93]
	s_mov_b64 s[8:9], s[90:91]
	v_readlane_b32 s27, v254, 61
	s_waitcnt vmcnt(0)
	s_barrier
	s_ashr_i32 s7, s6, 31
	s_lshr_b32 s14, s7, 28
	s_lshl_b32 s19, s1, 5
	s_add_i32 s14, s6, s14
	s_lshl_b32 s15, s0, 8
	s_ashr_i32 s14, s14, 4
	s_or_b32 s15, s15, s19
	v_lshl_or_b32 v132, v162, 3, s15
	s_mul_hi_i32 s15, s14, 0x9000
	s_mul_i32 s14, s14, 0x9000
	s_add_u32 s12, s12, s14
	s_addc_u32 s13, s13, s15
	v_ashrrev_i32_e32 v133, 31, v132
	v_lshl_add_u64 v[146:147], v[132:133], 2, s[12:13]
	s_lshl_b64 s[12:13], s[6:7], 19
	s_add_u32 s12, s26, s12
	s_addc_u32 s13, s27, s13
	v_ashrrev_i32_e32 v131, 31, v130
	global_load_dwordx4 v[134:137], v[146:147], off
	global_load_dwordx4 v[138:141], v[146:147], off offset:16
	global_load_dwordx4 v[142:145], v[146:147], off offset:512
	global_load_dwordx4 v[168:171], v[146:147], off offset:528
	v_lshl_add_u64 v[148:149], v[132:133], 1, s[12:13]
	v_lshlrev_b64 v[146:147], 11, v[130:131]
	v_lshl_add_u64 v[146:147], v[148:149], 0, v[146:147]
	global_load_dwordx4 v[172:175], v[146:147], off
	global_load_dwordx4 v[176:179], v[146:147], off offset:256
	v_mov_b32_e32 v248, v146
	v_mov_b32_e32 v249, v147
	s_mov_b32 s99, 0
	s_mov_b32 s98, 0x8000
	v_lshl_add_u64 v[246:247], v[248:249], 0, s[98:99]
	global_load_dwordx4 v[206:209], v[246:247], off
	global_load_dwordx4 v[210:213], v[246:247], off offset:256
	s_mov_b32 s98, 0x10000
	v_lshl_add_u64 v[246:247], v[248:249], 0, s[98:99]
	global_load_dwordx4 v[214:217], v[246:247], off
	global_load_dwordx4 v[218:221], v[246:247], off offset:256
	s_mov_b32 s98, 0x18000
	v_lshl_add_u64 v[246:247], v[248:249], 0, s[98:99]
	global_load_dwordx4 v[222:225], v[246:247], off
	global_load_dwordx4 v[226:229], v[246:247], off offset:256
	s_mov_b32 s98, 0x40000
	v_lshl_add_u64 v[246:247], v[248:249], 0, s[98:99]
	global_load_dwordx4 v[230:233], v[246:247], off
	global_load_dwordx4 v[234:237], v[246:247], off offset:256
	s_mov_b32 s98, 0x48000
	v_lshl_add_u64 v[246:247], v[248:249], 0, s[98:99]
	global_load_dwordx4 v[238:241], v[246:247], off
	global_load_dwordx4 v[242:245], v[246:247], off offset:256
	v_mbcnt_lo_u32_b32 v146, -1, 0
	v_mbcnt_hi_u32_b32 v163, -1, v146
	v_and_b32_e32 v147, 64, v163
	v_xor_b32_e32 v146, 16, v163
	v_add_u32_e32 v180, 64, v147
	v_cmp_lt_i32_e32 vcc, v146, v180
	s_lshl_b32 s1, s1, 2
	s_add_i32 s1, s1, 0
	v_cndmask_b32_e32 v146, v163, v146, vcc
	v_lshlrev_b32_e32 v167, 2, v146
	s_waitcnt vmcnt(10) lgkmcnt(0)
	v_pk_mul_f32 v[156:157], v[136:137], s[18:19] op_sel_hi:[1,0]
	v_pk_mul_f32 v[160:161], v[134:135], s[18:19] op_sel_hi:[1,0]
	v_pk_mul_f32 v[154:155], v[140:141], s[18:19] op_sel_hi:[1,0]
	v_pk_mul_f32 v[158:159], v[138:139], s[18:19] op_sel_hi:[1,0]
	v_pk_mul_f32 v[152:153], s[18:19], v[144:145] op_sel_hi:[0,1]
	v_pk_mul_f32 v[150:151], s[18:19], v[142:143] op_sel_hi:[0,1]
	v_lshlrev_b32_e32 v134, 16, v172
	v_and_b32_e32 v135, 0xffff0000, v172
	v_lshlrev_b32_e32 v136, 16, v173
	v_and_b32_e32 v137, 0xffff0000, v173
	v_lshlrev_b32_e32 v138, 16, v174
	v_and_b32_e32 v139, 0xffff0000, v174
	v_lshlrev_b32_e32 v140, 16, v175
	v_and_b32_e32 v141, 0xffff0000, v175
	v_pk_mul_f32 v[146:147], s[18:19], v[170:171] op_sel_hi:[0,1]
	v_pk_mul_f32 v[144:145], s[18:19], v[168:169] op_sel_hi:[0,1]
	v_lshlrev_b32_e32 v142, 16, v176
	v_and_b32_e32 v143, 0xffff0000, v176
	v_lshlrev_b32_e32 v164, 16, v177
	v_and_b32_e32 v165, 0xffff0000, v177
	v_lshlrev_b32_e32 v168, 16, v178
	v_and_b32_e32 v169, 0xffff0000, v178
	v_lshlrev_b32_e32 v170, 16, v179
	v_and_b32_e32 v171, 0xffff0000, v179
	v_pk_fma_f32 v[126:127], v[126:127], v[156:157], v[136:137]
	v_pk_fma_f32 v[124:125], v[124:125], v[160:161], v[134:135]
	v_pk_fma_f32 v[122:123], v[122:123], v[154:155], v[140:141]
	v_pk_fma_f32 v[120:121], v[120:121], v[158:159], v[138:139]
	v_pk_fma_f32 v[118:119], v[118:119], v[152:153], v[164:165]
	v_pk_fma_f32 v[116:117], v[116:117], v[150:151], v[142:143]
	v_pk_fma_f32 v[114:115], v[114:115], v[146:147], v[170:171]
	v_pk_fma_f32 v[112:113], v[112:113], v[144:145], v[168:169]
	v_mul_f32_e32 v134, v125, v125
	v_mul_f32_e32 v135, v127, v127
	v_mul_f32_e32 v136, v121, v121
	v_mul_f32_e32 v137, v123, v123
	v_mul_f32_e32 v138, v117, v117
	v_mul_f32_e32 v139, v119, v119
	v_mul_f32_e32 v140, v113, v113
	v_mul_f32_e32 v141, v115, v115
	v_fmac_f32_e32 v134, v124, v124
	v_fmac_f32_e32 v135, v126, v126
	v_fmac_f32_e32 v136, v120, v120
	v_fmac_f32_e32 v137, v122, v122
	v_fmac_f32_e32 v138, v116, v116
	v_fmac_f32_e32 v139, v118, v118
	v_fmac_f32_e32 v140, v112, v112
	v_add_f32_e32 v134, v134, v135
	v_add_f32_e32 v135, v136, v137
	v_fmac_f32_e32 v141, v114, v114
	v_add_f32_e32 v136, v138, v139
	v_add_f32_e32 v134, v134, v135
	v_add_f32_e32 v135, v140, v141
	v_add_f32_e32 v135, v136, v135
	v_add_f32_e32 v134, v134, v135
	ds_bpermute_b32 v135, v167, v134
	v_xor_b32_e32 v136, 32, v163
	v_cmp_lt_i32_e32 vcc, v136, v180
	s_waitcnt lgkmcnt(0)
	v_add_f32_e32 v134, v134, v135
	v_cndmask_b32_e32 v136, v163, v136, vcc
	v_lshlrev_b32_e32 v168, 2, v136
	ds_bpermute_b32 v135, v168, v134
	v_cmp_eq_u32_e32 vcc, 0, v162
	s_and_saveexec_b64 s[18:19], vcc
	s_cbranch_execz .LBB0_1402
	v_lshl_add_u32 v136, v130, 4, s1
	s_waitcnt lgkmcnt(0)
	v_add_f32_e32 v134, v134, v135
	ds_write_b32 v136, v134
;     __device__ __forceinline__ void fused(f32x4 (&acc)[2][2][4][2], const Unit& u, int wr, int wc, int fr, int fq, LAS unsigned char* lds, int tid) const {
;     ...
;                 for (int m = 0; m < 4; ++m) { const size_t off = (size_t)(ai * HALF + wr * 64 + m * 16 + fr) * DM + col0; float q = 0.f;
; #pragma unroll
;                     for (int bj = 0; bj < 2; ++bj) { f32x4 b0, b1;
;                         if (BBF) { const u32x4 w = *(const u32x4*)(xb_ + off + bj * HALF);
;                             b0 = (f32x4){__uint_as_float(w.x << 16), __uint_as_float(w.x & 0xffff0000u), __uint_as_float(w.y << 16), __uint_as_float(w.y & 0xffff0000u)};
;                             b1 = (f32x4){__uint_as_float(w.z << 16), __uint_as_float(w.z & 0xffff0000u), __uint_as_float(w.w << 16), __uint_as_float(w.w & 0xffff0000u)}; }
;                         else { b0 = __builtin_nontemporal_load((const f32x4*)(bs_ + off + bj * HALF)); b1 = __builtin_nontemporal_load((const f32x4*)(bs_ + off + bj * HALF + 4)); }
;                         const f32x4 x0 = b0 + gv[bj][0] * acc[ai][bj][m][0], x1 = b1 + gv[bj][1] * acc[ai][bj][m][1]; acc[ai][bj][m][0] = x0; acc[ai][bj][m][1] = x1;
;                         q += ((x0[0] * x0[0] + x0[1] * x0[1]) + (x0[2] * x0[2] + x0[3] * x0[3])) + ((x1[0] * x1[0] + x1[1] * x1[1]) + (x1[2] * x1[2] + x1[3] * x1[3])); }
;                     q += __shfl_xor(q, 16); q += __shfl_xor(q, 32);
;                     if (fq == 0) P[(ai * HALF + wr * 64 + m * 16 + fr) * 4 + wc] = q;
;                     asm volatile("" ::: "memory"); }
.LBB0_1402:
	s_or_b64 exec, exec, s[18:19]
	v_or_b32_e32 v134, 16, v130
	s_waitcnt lgkmcnt(0)
	v_ashrrev_i32_e32 v135, 31, v134
	v_lshlrev_b64 v[136:137], 11, v[134:135]
	v_lshl_add_u64 v[140:141], v[148:149], 0, v[136:137]
	s_waitcnt vmcnt(8) lgkmcnt(0)
	v_lshlrev_b32_e32 v162, 16, v206
	v_and_b32_e32 v163, 0xffff0000, v206
	v_lshlrev_b32_e32 v136, 16, v207
	v_and_b32_e32 v137, 0xffff0000, v207
	v_lshlrev_b32_e32 v164, 16, v208
	v_and_b32_e32 v165, 0xffff0000, v208
	v_lshlrev_b32_e32 v138, 16, v209
	v_and_b32_e32 v139, 0xffff0000, v209
	v_lshlrev_b32_e32 v170, 16, v210
	v_and_b32_e32 v171, 0xffff0000, v210
	v_lshlrev_b32_e32 v140, 16, v211
	v_and_b32_e32 v141, 0xffff0000, v211
	v_lshlrev_b32_e32 v172, 16, v212
	v_and_b32_e32 v173, 0xffff0000, v212
	v_lshlrev_b32_e32 v142, 16, v213
	v_and_b32_e32 v143, 0xffff0000, v213
	s_mov_b32 s98, 0x50000
	v_lshl_add_u64 v[246:247], v[248:249], 0, s[98:99]
	global_load_dwordx4 v[206:209], v[246:247], off
	global_load_dwordx4 v[210:213], v[246:247], off offset:256
	v_pk_fma_f32 v[110:111], v[110:111], v[156:157], v[136:137]
	v_pk_fma_f32 v[108:109], v[108:109], v[160:161], v[162:163]
	v_pk_fma_f32 v[106:107], v[106:107], v[154:155], v[138:139]
	v_pk_fma_f32 v[104:105], v[104:105], v[158:159], v[164:165]
	v_pk_fma_f32 v[102:103], v[102:103], v[152:153], v[140:141]
	v_pk_fma_f32 v[100:101], v[100:101], v[150:151], v[170:171]
	v_pk_fma_f32 v[98:99], v[98:99], v[146:147], v[142:143]
	v_pk_fma_f32 v[96:97], v[96:97], v[144:145], v[172:173]
	v_mul_f32_e32 v136, v109, v109
	v_mul_f32_e32 v137, v111, v111
	v_mul_f32_e32 v138, v105, v105
	v_mul_f32_e32 v139, v107, v107
	v_mul_f32_e32 v140, v101, v101
	v_mul_f32_e32 v141, v103, v103
	v_mul_f32_e32 v142, v97, v97
	v_mul_f32_e32 v143, v99, v99
	v_fmac_f32_e32 v136, v108, v108
	v_fmac_f32_e32 v137, v110, v110
	v_fmac_f32_e32 v138, v104, v104
	v_fmac_f32_e32 v139, v106, v106
	v_fmac_f32_e32 v140, v100, v100
	v_fmac_f32_e32 v141, v102, v102
	v_fmac_f32_e32 v142, v96, v96
	v_fmac_f32_e32 v143, v98, v98
	v_add_f32_e32 v136, v136, v137
	v_add_f32_e32 v137, v138, v139
	v_add_f32_e32 v138, v140, v141
	v_add_f32_e32 v139, v142, v143
	v_add_f32_e32 v136, v136, v137
	v_add_f32_e32 v137, v138, v139
	v_add_f32_e32 v136, v136, v137
	ds_bpermute_b32 v137, v167, v136
	s_waitcnt lgkmcnt(0)
	v_add_f32_e32 v136, v136, v137
	ds_bpermute_b32 v137, v168, v136
	s_and_saveexec_b64 s[18:19], vcc
	s_cbranch_execz .LBB0_1404
	v_lshl_add_u32 v138, v134, 4, s1
	s_waitcnt lgkmcnt(0)
	v_add_f32_e32 v136, v136, v137
	ds_write_b32 v138, v136
.LBB0_1404:
	s_or_b64 exec, exec, s[18:19]
	v_or_b32_e32 v136, 32, v130
	s_waitcnt lgkmcnt(0)
	v_ashrrev_i32_e32 v137, 31, v136
	v_lshlrev_b64 v[138:139], 11, v[136:137]
	v_lshl_add_u64 v[142:143], v[148:149], 0, v[138:139]
	s_waitcnt vmcnt(8) lgkmcnt(0)
	v_lshlrev_b32_e32 v142, 16, v214
	v_and_b32_e32 v143, 0xffff0000, v214
	v_lshlrev_b32_e32 v138, 16, v215
	v_and_b32_e32 v139, 0xffff0000, v215
	v_lshlrev_b32_e32 v170, 16, v216
	v_and_b32_e32 v171, 0xffff0000, v216
	v_lshlrev_b32_e32 v140, 16, v217
	v_and_b32_e32 v141, 0xffff0000, v217
	v_lshlrev_b32_e32 v172, 16, v218
	v_and_b32_e32 v173, 0xffff0000, v218
	v_lshlrev_b32_e32 v162, 16, v219
	v_and_b32_e32 v163, 0xffff0000, v219
	v_lshlrev_b32_e32 v174, 16, v220
	v_and_b32_e32 v175, 0xffff0000, v220
	v_lshlrev_b32_e32 v164, 16, v221
	v_and_b32_e32 v165, 0xffff0000, v221
	s_mov_b32 s98, 0x58000
	v_lshl_add_u64 v[246:247], v[248:249], 0, s[98:99]
	global_load_dwordx4 v[214:217], v[246:247], off
	global_load_dwordx4 v[218:221], v[246:247], off offset:256
	v_pk_fma_f32 v[94:95], v[94:95], v[156:157], v[138:139]
	v_pk_fma_f32 v[92:93], v[92:93], v[160:161], v[142:143]
	v_pk_fma_f32 v[90:91], v[90:91], v[154:155], v[140:141]
	v_pk_fma_f32 v[88:89], v[88:89], v[158:159], v[170:171]
	v_pk_fma_f32 v[86:87], v[86:87], v[152:153], v[162:163]
	v_pk_fma_f32 v[84:85], v[84:85], v[150:151], v[172:173]
	v_pk_fma_f32 v[82:83], v[82:83], v[146:147], v[164:165]
	v_pk_fma_f32 v[80:81], v[80:81], v[144:145], v[174:175]
	v_mul_f32_e32 v138, v93, v93
	v_mul_f32_e32 v139, v95, v95
	v_mul_f32_e32 v140, v89, v89
	v_mul_f32_e32 v141, v91, v91
	v_mul_f32_e32 v142, v85, v85
	v_mul_f32_e32 v143, v87, v87
	v_mul_f32_e32 v162, v81, v81
	v_mul_f32_e32 v163, v83, v83
	v_fmac_f32_e32 v138, v92, v92
	v_fmac_f32_e32 v139, v94, v94
	v_fmac_f32_e32 v140, v88, v88
	v_fmac_f32_e32 v141, v90, v90
	v_fmac_f32_e32 v142, v84, v84
	v_fmac_f32_e32 v143, v86, v86
	v_fmac_f32_e32 v162, v80, v80
	v_fmac_f32_e32 v163, v82, v82
	v_add_f32_e32 v138, v138, v139
	v_add_f32_e32 v139, v140, v141
	v_add_f32_e32 v140, v142, v143
	v_add_f32_e32 v141, v162, v163
	v_add_f32_e32 v138, v138, v139
	v_add_f32_e32 v139, v140, v141
	v_add_f32_e32 v138, v138, v139
	ds_bpermute_b32 v139, v167, v138
	s_waitcnt lgkmcnt(0)
	v_add_f32_e32 v138, v138, v139
	ds_bpermute_b32 v139, v168, v138
	s_and_saveexec_b64 s[18:19], vcc
	s_cbranch_execz .LBB0_1406
	v_lshl_add_u32 v140, v136, 4, s1
	s_waitcnt lgkmcnt(0)
	v_add_f32_e32 v138, v138, v139
	ds_write_b32 v140, v138
;     __device__ __forceinline__ void fused(f32x4 (&acc)[2][2][4][2], const Unit& u, int wr, int wc, int fr, int fq, LAS unsigned char* lds, int tid) const {
;     ...
;                 for (int m = 0; m < 4; ++m) { const size_t off = (size_t)(ai * HALF + wr * 64 + m * 16 + fr) * DM + col0; float q = 0.f;
; #pragma unroll
;                     for (int bj = 0; bj < 2; ++bj) { f32x4 b0, b1;
;                         if (BBF) { const u32x4 w = *(const u32x4*)(xb_ + off + bj * HALF);
;                             b0 = (f32x4){__uint_as_float(w.x << 16), __uint_as_float(w.x & 0xffff0000u), __uint_as_float(w.y << 16), __uint_as_float(w.y & 0xffff0000u)};
;                             b1 = (f32x4){__uint_as_float(w.z << 16), __uint_as_float(w.z & 0xffff0000u), __uint_as_float(w.w << 16), __uint_as_float(w.w & 0xffff0000u)}; }
;                         else { b0 = __builtin_nontemporal_load((const f32x4*)(bs_ + off + bj * HALF)); b1 = __builtin_nontemporal_load((const f32x4*)(bs_ + off + bj * HALF + 4)); }
;                         const f32x4 x0 = b0 + gv[bj][0] * acc[ai][bj][m][0], x1 = b1 + gv[bj][1] * acc[ai][bj][m][1]; acc[ai][bj][m][0] = x0; acc[ai][bj][m][1] = x1;
;                         q += ((x0[0] * x0[0] + x0[1] * x0[1]) + (x0[2] * x0[2] + x0[3] * x0[3])) + ((x1[0] * x1[0] + x1[1] * x1[1]) + (x1[2] * x1[2] + x1[3] * x1[3])); }
;                     q += __shfl_xor(q, 16); q += __shfl_xor(q, 32);
;                     if (fq == 0) P[(ai * HALF + wr * 64 + m * 16 + fr) * 4 + wc] = q;
;                     asm volatile("" ::: "memory"); }
.LBB0_1406:
	s_or_b64 exec, exec, s[18:19]
	v_or_b32_e32 v138, 48, v130
	s_waitcnt lgkmcnt(0)
	v_ashrrev_i32_e32 v139, 31, v138
	v_lshlrev_b64 v[140:141], 11, v[138:139]
	v_lshl_add_u64 v[162:163], v[148:149], 0, v[140:141]
	s_waitcnt vmcnt(8) lgkmcnt(0)
	v_lshlrev_b32_e32 v170, 16, v222
	v_and_b32_e32 v171, 0xffff0000, v222
	v_lshlrev_b32_e32 v140, 16, v223
	v_and_b32_e32 v141, 0xffff0000, v223
	v_lshlrev_b32_e32 v172, 16, v224
	v_and_b32_e32 v173, 0xffff0000, v224
	v_lshlrev_b32_e32 v142, 16, v225
	v_and_b32_e32 v143, 0xffff0000, v225
	v_lshlrev_b32_e32 v174, 16, v226
	v_and_b32_e32 v175, 0xffff0000, v226
	v_lshlrev_b32_e32 v162, 16, v227
	v_and_b32_e32 v163, 0xffff0000, v227
	v_lshlrev_b32_e32 v176, 16, v228
	v_and_b32_e32 v177, 0xffff0000, v228
	v_lshlrev_b32_e32 v164, 16, v229
	v_and_b32_e32 v165, 0xffff0000, v229
	v_pk_fma_f32 v[78:79], v[78:79], v[156:157], v[140:141]
	v_pk_fma_f32 v[76:77], v[76:77], v[160:161], v[170:171]
	v_pk_fma_f32 v[74:75], v[74:75], v[154:155], v[142:143]
	v_pk_fma_f32 v[72:73], v[72:73], v[158:159], v[172:173]
	v_pk_fma_f32 v[70:71], v[70:71], v[152:153], v[162:163]
	v_pk_fma_f32 v[68:69], v[68:69], v[150:151], v[174:175]
	v_pk_fma_f32 v[66:67], v[66:67], v[146:147], v[164:165]
	v_pk_fma_f32 v[64:65], v[64:65], v[144:145], v[176:177]
	v_mul_f32_e32 v140, v77, v77
	v_mul_f32_e32 v141, v79, v79
	v_mul_f32_e32 v142, v73, v73
	v_mul_f32_e32 v143, v75, v75
	v_mul_f32_e32 v162, v69, v69
	v_mul_f32_e32 v163, v71, v71
	v_mul_f32_e32 v164, v65, v65
	v_mul_f32_e32 v165, v67, v67
	v_fmac_f32_e32 v140, v76, v76
	v_fmac_f32_e32 v141, v78, v78
	v_fmac_f32_e32 v142, v72, v72
	v_fmac_f32_e32 v143, v74, v74
	v_fmac_f32_e32 v162, v68, v68
	v_fmac_f32_e32 v163, v70, v70
	v_fmac_f32_e32 v164, v64, v64
	v_fmac_f32_e32 v165, v66, v66
	v_add_f32_e32 v140, v140, v141
	v_add_f32_e32 v141, v142, v143
	v_add_f32_e32 v142, v162, v163
	v_add_f32_e32 v143, v164, v165
	v_add_f32_e32 v140, v140, v141
	v_add_f32_e32 v141, v142, v143
	v_add_f32_e32 v140, v140, v141
	ds_bpermute_b32 v141, v167, v140
	s_waitcnt lgkmcnt(0)
	v_add_f32_e32 v140, v140, v141
	ds_bpermute_b32 v141, v168, v140
	s_and_saveexec_b64 s[18:19], vcc
	s_cbranch_execz .LBB0_1408
	v_lshl_add_u32 v142, v138, 4, s1
	s_waitcnt lgkmcnt(0)
	v_add_f32_e32 v140, v140, v141
	ds_write_b32 v142, v140
.LBB0_1408:
	s_or_b64 exec, exec, s[18:19]
	v_add_u32_e32 v140, 0x80, v130
	s_waitcnt lgkmcnt(0)
	v_ashrrev_i32_e32 v141, 31, v140
	v_lshlrev_b64 v[142:143], 11, v[140:141]
	v_lshl_add_u64 v[142:143], v[148:149], 0, v[142:143]
	s_waitcnt vmcnt(6) lgkmcnt(0)
	v_lshlrev_b32_e32 v142, 16, v230
	v_and_b32_e32 v143, 0xffff0000, v230
	v_lshlrev_b32_e32 v162, 16, v231
	v_and_b32_e32 v163, 0xffff0000, v231
	v_lshlrev_b32_e32 v174, 16, v232
	v_and_b32_e32 v175, 0xffff0000, v232
	v_lshlrev_b32_e32 v164, 16, v233
	v_and_b32_e32 v165, 0xffff0000, v233
	v_lshlrev_b32_e32 v176, 16, v234
	v_and_b32_e32 v177, 0xffff0000, v234
	v_lshlrev_b32_e32 v170, 16, v235
	v_and_b32_e32 v171, 0xffff0000, v235
	v_lshlrev_b32_e32 v178, 16, v236
	v_and_b32_e32 v179, 0xffff0000, v236
	v_lshlrev_b32_e32 v172, 16, v237
	v_and_b32_e32 v173, 0xffff0000, v237
	v_pk_fma_f32 v[62:63], v[62:63], v[156:157], v[162:163]
	v_pk_fma_f32 v[60:61], v[60:61], v[160:161], v[142:143]
	v_pk_fma_f32 v[58:59], v[58:59], v[154:155], v[164:165]
	v_pk_fma_f32 v[56:57], v[56:57], v[158:159], v[174:175]
	v_pk_fma_f32 v[54:55], v[54:55], v[152:153], v[170:171]
	v_pk_fma_f32 v[52:53], v[52:53], v[150:151], v[176:177]
	v_pk_fma_f32 v[50:51], v[50:51], v[146:147], v[172:173]
	v_pk_fma_f32 v[48:49], v[48:49], v[144:145], v[178:179]
	v_mul_f32_e32 v142, v61, v61
	v_mul_f32_e32 v143, v63, v63
	v_mul_f32_e32 v162, v57, v57
	v_mul_f32_e32 v163, v59, v59
	v_mul_f32_e32 v164, v53, v53
	v_mul_f32_e32 v165, v55, v55
	v_mul_f32_e32 v169, v49, v49
	v_mul_f32_e32 v170, v51, v51
	v_fmac_f32_e32 v142, v60, v60
	v_fmac_f32_e32 v143, v62, v62
	v_fmac_f32_e32 v162, v56, v56
	v_fmac_f32_e32 v163, v58, v58
	v_fmac_f32_e32 v164, v52, v52
	v_fmac_f32_e32 v165, v54, v54
	v_fmac_f32_e32 v169, v48, v48
	v_fmac_f32_e32 v170, v50, v50
	v_add_f32_e32 v142, v142, v143
	v_add_f32_e32 v143, v162, v163
	v_add_f32_e32 v162, v164, v165
	v_add_f32_e32 v163, v169, v170
	v_add_f32_e32 v142, v142, v143
	v_add_f32_e32 v143, v162, v163
	v_add_f32_e32 v142, v142, v143
	ds_bpermute_b32 v143, v167, v142
	s_waitcnt lgkmcnt(0)
	v_add_f32_e32 v142, v142, v143
	ds_bpermute_b32 v143, v168, v142
	s_and_saveexec_b64 s[18:19], vcc
	s_cbranch_execz .LBB0_1410
	v_lshl_add_u32 v162, v140, 4, s1
	s_waitcnt lgkmcnt(0)
	v_add_f32_e32 v142, v142, v143
	ds_write_b32 v162, v142
;     __device__ __forceinline__ void fused(f32x4 (&acc)[2][2][4][2], const Unit& u, int wr, int wc, int fr, int fq, LAS unsigned char* lds, int tid) const {
;     ...
;                 for (int m = 0; m < 4; ++m) { const size_t off = (size_t)(ai * HALF + wr * 64 + m * 16 + fr) * DM + col0; float q = 0.f;
; #pragma unroll
;                     for (int bj = 0; bj < 2; ++bj) { f32x4 b0, b1;
;                         if (BBF) { const u32x4 w = *(const u32x4*)(xb_ + off + bj * HALF);
;                             b0 = (f32x4){__uint_as_float(w.x << 16), __uint_as_float(w.x & 0xffff0000u), __uint_as_float(w.y << 16), __uint_as_float(w.y & 0xffff0000u)};
;                             b1 = (f32x4){__uint_as_float(w.z << 16), __uint_as_float(w.z & 0xffff0000u), __uint_as_float(w.w << 16), __uint_as_float(w.w & 0xffff0000u)}; }
;                         else { b0 = __builtin_nontemporal_load((const f32x4*)(bs_ + off + bj * HALF)); b1 = __builtin_nontemporal_load((const f32x4*)(bs_ + off + bj * HALF + 4)); }
;                         const f32x4 x0 = b0 + gv[bj][0] * acc[ai][bj][m][0], x1 = b1 + gv[bj][1] * acc[ai][bj][m][1]; acc[ai][bj][m][0] = x0; acc[ai][bj][m][1] = x1;
;                         q += ((x0[0] * x0[0] + x0[1] * x0[1]) + (x0[2] * x0[2] + x0[3] * x0[3])) + ((x1[0] * x1[0] + x1[1] * x1[1]) + (x1[2] * x1[2] + x1[3] * x1[3])); }
;                     q += __shfl_xor(q, 16); q += __shfl_xor(q, 32);
;                     if (fq == 0) P[(ai * HALF + wr * 64 + m * 16 + fr) * 4 + wc] = q;
;                     asm volatile("" ::: "memory"); }
.LBB0_1410:
	s_or_b64 exec, exec, s[18:19]
	v_add_u32_e32 v142, 0x90, v130
	s_waitcnt lgkmcnt(0)
	v_ashrrev_i32_e32 v143, 31, v142
	v_lshlrev_b64 v[162:163], 11, v[142:143]
	v_lshl_add_u64 v[170:171], v[148:149], 0, v[162:163]
	s_waitcnt vmcnt(4) lgkmcnt(0)
	v_lshlrev_b32_e32 v174, 16, v238
	v_and_b32_e32 v175, 0xffff0000, v238
	v_lshlrev_b32_e32 v162, 16, v239
	v_and_b32_e32 v163, 0xffff0000, v239
	v_lshlrev_b32_e32 v176, 16, v240
	v_and_b32_e32 v177, 0xffff0000, v240
	v_lshlrev_b32_e32 v164, 16, v241
	v_and_b32_e32 v165, 0xffff0000, v241
	v_lshlrev_b32_e32 v178, 16, v242
	v_and_b32_e32 v179, 0xffff0000, v242
	v_lshlrev_b32_e32 v170, 16, v243
	v_and_b32_e32 v171, 0xffff0000, v243
	v_lshlrev_b32_e32 v180, 16, v244
	v_and_b32_e32 v181, 0xffff0000, v244
	v_lshlrev_b32_e32 v172, 16, v245
	v_and_b32_e32 v173, 0xffff0000, v245
	v_pk_fma_f32 v[46:47], v[46:47], v[156:157], v[162:163]
	v_pk_fma_f32 v[44:45], v[44:45], v[160:161], v[174:175]
	v_pk_fma_f32 v[42:43], v[42:43], v[154:155], v[164:165]
	v_pk_fma_f32 v[40:41], v[40:41], v[158:159], v[176:177]
	v_pk_fma_f32 v[38:39], v[38:39], v[152:153], v[170:171]
	v_pk_fma_f32 v[36:37], v[36:37], v[150:151], v[178:179]
	v_pk_fma_f32 v[34:35], v[34:35], v[146:147], v[172:173]
	v_pk_fma_f32 v[32:33], v[32:33], v[144:145], v[180:181]
	v_mul_f32_e32 v162, v45, v45
	v_mul_f32_e32 v163, v47, v47
	v_mul_f32_e32 v164, v41, v41
	v_mul_f32_e32 v165, v43, v43
	v_mul_f32_e32 v169, v37, v37
	v_mul_f32_e32 v170, v39, v39
	v_mul_f32_e32 v171, v33, v33
	v_mul_f32_e32 v172, v35, v35
	v_fmac_f32_e32 v162, v44, v44
	v_fmac_f32_e32 v163, v46, v46
	v_fmac_f32_e32 v164, v40, v40
	v_fmac_f32_e32 v165, v42, v42
	v_fmac_f32_e32 v169, v36, v36
	v_fmac_f32_e32 v170, v38, v38
	v_fmac_f32_e32 v171, v32, v32
	v_fmac_f32_e32 v172, v34, v34
	v_add_f32_e32 v162, v162, v163
	v_add_f32_e32 v163, v164, v165
	v_add_f32_e32 v164, v169, v170
	v_add_f32_e32 v165, v171, v172
	v_add_f32_e32 v162, v162, v163
	v_add_f32_e32 v163, v164, v165
	v_add_f32_e32 v162, v162, v163
	ds_bpermute_b32 v163, v167, v162
	s_waitcnt lgkmcnt(0)
	v_add_f32_e32 v162, v162, v163
	ds_bpermute_b32 v163, v168, v162
	s_and_saveexec_b64 s[18:19], vcc
	s_cbranch_execz .LBB0_1412
	v_lshl_add_u32 v164, v142, 4, s1
	s_waitcnt lgkmcnt(0)
	v_add_f32_e32 v162, v162, v163
	ds_write_b32 v164, v162
.LBB0_1412:
	s_or_b64 exec, exec, s[18:19]
	v_add_u32_e32 v162, 0xa0, v130
	s_waitcnt lgkmcnt(0)
	v_ashrrev_i32_e32 v163, 31, v162
	v_lshlrev_b64 v[164:165], 11, v[162:163]
	v_lshl_add_u64 v[164:165], v[148:149], 0, v[164:165]
	s_waitcnt vmcnt(2) lgkmcnt(0)
	v_lshlrev_b32_e32 v164, 16, v206
	v_and_b32_e32 v165, 0xffff0000, v206
	v_lshlrev_b32_e32 v170, 16, v207
	v_and_b32_e32 v171, 0xffff0000, v207
	v_lshlrev_b32_e32 v178, 16, v208
	v_and_b32_e32 v179, 0xffff0000, v208
	v_lshlrev_b32_e32 v172, 16, v209
	v_and_b32_e32 v173, 0xffff0000, v209
	v_lshlrev_b32_e32 v180, 16, v210
	v_and_b32_e32 v181, 0xffff0000, v210
	v_lshlrev_b32_e32 v174, 16, v211
	v_and_b32_e32 v175, 0xffff0000, v211
	v_lshlrev_b32_e32 v182, 16, v212
	v_and_b32_e32 v183, 0xffff0000, v212
	v_lshlrev_b32_e32 v176, 16, v213
	v_and_b32_e32 v177, 0xffff0000, v213
	v_pk_fma_f32 v[30:31], v[30:31], v[156:157], v[170:171]
	v_pk_fma_f32 v[28:29], v[28:29], v[160:161], v[164:165]
	v_pk_fma_f32 v[26:27], v[26:27], v[154:155], v[172:173]
	v_pk_fma_f32 v[24:25], v[24:25], v[158:159], v[178:179]
	v_pk_fma_f32 v[22:23], v[22:23], v[152:153], v[174:175]
	v_pk_fma_f32 v[20:21], v[20:21], v[150:151], v[180:181]
	v_pk_fma_f32 v[18:19], v[18:19], v[146:147], v[176:177]
	v_pk_fma_f32 v[16:17], v[16:17], v[144:145], v[182:183]
	v_mul_f32_e32 v164, v29, v29
	v_mul_f32_e32 v165, v31, v31
	v_mul_f32_e32 v169, v25, v25
	v_mul_f32_e32 v170, v27, v27
	v_mul_f32_e32 v171, v21, v21
	v_mul_f32_e32 v172, v23, v23
	v_mul_f32_e32 v173, v17, v17
	v_mul_f32_e32 v174, v19, v19
	v_fmac_f32_e32 v164, v28, v28
	v_fmac_f32_e32 v165, v30, v30
	v_fmac_f32_e32 v169, v24, v24
	v_fmac_f32_e32 v170, v26, v26
	v_fmac_f32_e32 v171, v20, v20
	v_fmac_f32_e32 v172, v22, v22
	v_fmac_f32_e32 v173, v16, v16
	v_fmac_f32_e32 v174, v18, v18
	v_add_f32_e32 v164, v164, v165
	v_add_f32_e32 v165, v169, v170
	v_add_f32_e32 v169, v171, v172
	v_add_f32_e32 v170, v173, v174
	v_add_f32_e32 v164, v164, v165
	v_add_f32_e32 v165, v169, v170
	v_add_f32_e32 v164, v164, v165
	ds_bpermute_b32 v165, v167, v164
	s_waitcnt lgkmcnt(0)
	v_add_f32_e32 v164, v164, v165
	ds_bpermute_b32 v165, v168, v164
	s_and_saveexec_b64 s[18:19], vcc
	s_cbranch_execz .LBB0_1414
	v_lshl_add_u32 v169, v162, 4, s1
	s_waitcnt lgkmcnt(0)
	v_add_f32_e32 v164, v164, v165
	ds_write_b32 v169, v164
.LBB0_1414:
	s_or_b64 exec, exec, s[18:19]
	v_add_u32_e32 v164, 0xb0, v130
	s_waitcnt lgkmcnt(0)
	v_ashrrev_i32_e32 v165, 31, v164
	v_lshlrev_b64 v[170:171], 11, v[164:165]
	v_lshl_add_u64 v[148:149], v[148:149], 0, v[170:171]
	s_waitcnt vmcnt(0) lgkmcnt(0)
	v_lshlrev_b32_e32 v148, 16, v214
	v_and_b32_e32 v149, 0xffff0000, v214
	v_lshlrev_b32_e32 v170, 16, v215
	v_and_b32_e32 v171, 0xffff0000, v215
	v_lshlrev_b32_e32 v178, 16, v216
	v_and_b32_e32 v179, 0xffff0000, v216
	v_lshlrev_b32_e32 v172, 16, v217
	v_and_b32_e32 v173, 0xffff0000, v217
	v_lshlrev_b32_e32 v180, 16, v218
	v_and_b32_e32 v181, 0xffff0000, v218
	v_lshlrev_b32_e32 v174, 16, v219
	v_and_b32_e32 v175, 0xffff0000, v219
	v_lshlrev_b32_e32 v182, 16, v220
	v_and_b32_e32 v183, 0xffff0000, v220
	v_lshlrev_b32_e32 v176, 16, v221
	v_and_b32_e32 v177, 0xffff0000, v221
	v_pk_fma_f32 v[156:157], v[14:15], v[156:157], v[170:171]
	v_pk_fma_f32 v[160:161], v[12:13], v[160:161], v[148:149]
	v_pk_fma_f32 v[148:149], v[10:11], v[154:155], v[172:173]
	v_pk_fma_f32 v[154:155], v[8:9], v[158:159], v[178:179]
	v_pk_fma_f32 v[8:9], v[6:7], v[152:153], v[174:175]
	v_pk_fma_f32 v[12:13], v[4:5], v[150:151], v[180:181]
	v_pk_fma_f32 v[10:11], v[2:3], v[146:147], v[176:177]
	v_pk_fma_f32 v[14:15], v[0:1], v[144:145], v[182:183]
	v_mul_f32_e32 v0, v161, v161
	v_mul_f32_e32 v1, v157, v157
	v_mul_f32_e32 v2, v155, v155
	v_mul_f32_e32 v3, v149, v149
	v_mul_f32_e32 v4, v13, v13
	v_mul_f32_e32 v5, v9, v9
	v_mul_f32_e32 v6, v15, v15
	v_mul_f32_e32 v7, v11, v11
	v_fmac_f32_e32 v0, v160, v160
	v_fmac_f32_e32 v1, v156, v156
	v_fmac_f32_e32 v2, v154, v154
	v_fmac_f32_e32 v3, v148, v148
	v_fmac_f32_e32 v4, v12, v12
	v_fmac_f32_e32 v5, v8, v8
	v_fmac_f32_e32 v6, v14, v14
	v_fmac_f32_e32 v7, v10, v10
	v_add_f32_e32 v0, v0, v1
	v_add_f32_e32 v1, v2, v3
	v_add_f32_e32 v2, v4, v5
	v_add_f32_e32 v3, v6, v7
	v_add_f32_e32 v0, v0, v1
	v_add_f32_e32 v1, v2, v3
	v_add_f32_e32 v0, v0, v1
	ds_bpermute_b32 v1, v167, v0
	s_waitcnt lgkmcnt(0)
	v_add_f32_e32 v0, v0, v1
	ds_bpermute_b32 v1, v168, v0
	s_and_saveexec_b64 s[18:19], vcc
	s_cbranch_execz .LBB0_1416
	v_lshl_add_u32 v2, v164, 4, s1
	s_waitcnt lgkmcnt(0)
	v_add_f32_e32 v0, v0, v1
	ds_write_b32 v2, v0

;     __device__ __forceinline__ void fused(f32x4 (&acc)[2][2][4][2], const Unit& u, int wr, int wc, int fr, int fq, LAS unsigned char* lds, int tid) const {
;     ...
;         if (tid == 0) { __hip_atomic_fetch_add(cnt + u.pm, 1u, __ATOMIC_RELAXED, __HIP_MEMORY_SCOPE_AGENT);
;             unsigned sp = 0; while (__hip_atomic_load(cnt + u.pm, __ATOMIC_RELAXED, __HIP_MEMORY_SCOPE_AGENT) < 4u) { __builtin_amdgcn_s_sleep(1); if (++sp > (1u << 24)) break; }
;             __builtin_amdgcn_fence(__ATOMIC_ACQUIRE, "agent"); asm volatile("s_waitcnt vmcnt(0)" ::: "memory"); }
.LBB0_1440:
	s_or_b64 exec, exec, s[16:17]
	s_nop 0
	s_waitcnt vmcnt(0)

; __global__ void __launch_bounds__(512, 2) mk_fwd(Args A) {
	.amdhsa_kernel _Z6mk_fwd4Args
		.amdhsa_group_segment_fixed_size 0
		.amdhsa_private_segment_fixed_size 0
		.amdhsa_kernarg_size 472
		.amdhsa_user_sgpr_count 2
		.amdhsa_user_sgpr_dispatch_ptr 0
		.amdhsa_user_sgpr_queue_ptr 0
		.amdhsa_user_sgpr_kernarg_segment_ptr 1
		.amdhsa_user_sgpr_dispatch_id 0
		.amdhsa_user_sgpr_kernarg_preload_length 0
		.amdhsa_user_sgpr_kernarg_preload_offset 0
		.amdhsa_user_sgpr_private_segment_size 0
		.amdhsa_uses_dynamic_stack 0
		.amdhsa_enable_private_segment 0
		.amdhsa_system_sgpr_workgroup_id_x 1
		.amdhsa_system_sgpr_workgroup_id_y 0
		.amdhsa_system_sgpr_workgroup_id_z 0
		.amdhsa_system_sgpr_workgroup_info 0
		.amdhsa_system_vgpr_workitem_id 2
		.amdhsa_next_free_vgpr 256
		.amdhsa_next_free_sgpr 100
		.amdhsa_accum_offset 256
		.amdhsa_reserve_vcc 1
		.amdhsa_float_round_mode_32 0
		.amdhsa_float_round_mode_16_64 0
		.amdhsa_float_denorm_mode_32 3
		.amdhsa_float_denorm_mode_16_64 3
		.amdhsa_dx10_clamp 1
		.amdhsa_ieee_mode 1
		.amdhsa_fp16_overflow 0
		.amdhsa_tg_split 0
		.amdhsa_exception_fp_ieee_invalid_op 0
		.amdhsa_exception_fp_denorm_src 0
		.amdhsa_exception_fp_ieee_div_zero 0
		.amdhsa_exception_fp_ieee_overflow 0
		.amdhsa_exception_fp_ieee_underflow 0
		.amdhsa_exception_fp_ieee_inexact 0
		.amdhsa_exception_int_div_zero 0
	.end_amdhsa_kernel

; __global__ void __launch_bounds__(512, 2) mk_fwd(Args A) {
amdhsa.kernels:
  - .agpr_count:     0
    .args:
      - .offset:         0
        .size:           216
        .value_kind:     by_value
      - .offset:         216
        .size:           4
        .value_kind:     hidden_block_count_x
      - .offset:         220
        .size:           4
        .value_kind:     hidden_block_count_y
      - .offset:         224
        .size:           4
        .value_kind:     hidden_block_count_z
      - .offset:         228
        .size:           2
        .value_kind:     hidden_group_size_x
      - .offset:         230
        .size:           2
        .value_kind:     hidden_group_size_y
      - .offset:         232
        .size:           2
        .value_kind:     hidden_group_size_z
      - .offset:         234
        .size:           2
        .value_kind:     hidden_remainder_x
      - .offset:         236
        .size:           2
        .value_kind:     hidden_remainder_y
      - .offset:         238
        .size:           2
        .value_kind:     hidden_remainder_z
      - .offset:         256
        .size:           8
        .value_kind:     hidden_global_offset_x
      - .offset:         264
        .size:           8
        .value_kind:     hidden_global_offset_y
      - .offset:         272
        .size:           8
        .value_kind:     hidden_global_offset_z
      - .offset:         280
        .size:           2
        .value_kind:     hidden_grid_dims
      - .offset:         304
        .size:           8
        .value_kind:     hidden_multigrid_sync_arg
      - .offset:         336
        .size:           4
        .value_kind:     hidden_dynamic_lds_size
    .group_segment_fixed_size: 0
    .kernarg_segment_align: 8
    .kernarg_segment_size: 472
    .language:       OpenCL C
    .language_version:
      - 2
      - 0
    .max_flat_workgroup_size: 512
    .name:           _Z6mk_fwd4Args
    .private_segment_fixed_size: 0
    .sgpr_count:     106
    .sgpr_spill_count: 107
    .symbol:         _Z6mk_fwd4Args.kd
    .uniform_work_group_size: 1
    .uses_dynamic_stack: false
    .vgpr_count:     256
    .vgpr_spill_count: 0
    .wavefront_size: 64
